# P4 chain loop: tile prefetch loads and o stores use scalar bases with fixed per-thread offsets instead of per-step 64-bit VGPR address arithmetic
# speedup vs baseline: 1.0047x; 1.0001x over previous
.LBB0_610:
	s_or_b64 exec, exec, s[8:9]
	v_or_b32_e32 v75, s24, v93
	s_movk_i32 s6, 0x90
	v_mul_lo_u32 v75, v75, s6
	v_add_u32_e32 v75, s46, v75
	v_and_b32_e32 v193, 48, v0
	v_lshlrev_b32_e32 v180, 5, v74
	s_waitcnt lgkmcnt(0)
	s_barrier
	v_add_u32_e32 v179, v75, v193
	v_add_u32_e32 v74, 0, v180
	v_add_u32_e32 v89, 0x1d500, v74
	ds_read_b128 v[74:77], v179
	ds_read_b128 v[96:99], v89
	ds_read_b128 v[100:103], v89 offset:16
	ds_read_b128 v[78:81], v179 offset:64
	v_add_u32_e32 v196, 0, v193
	v_mad_u32_u24 v91, v93, s6, v196
	v_add_u32_e32 v183, v174, v87
	s_waitcnt lgkmcnt(3)
	v_lshlrev_b32_e32 v104, 16, v74
	v_and_b32_e32 v105, 0xffff0000, v74
	s_waitcnt lgkmcnt(2)
	v_pk_mul_f32 v[96:97], v[96:97], v[104:105]
	v_lshlrev_b32_e32 v104, 16, v75
	v_and_b32_e32 v105, 0xffff0000, v75
	v_pk_mul_f32 v[98:99], v[98:99], v[104:105]
	v_cvt_pk_bf16_f32 v96, v96, v97
	v_cvt_pk_bf16_f32 v97, v98, v99
	v_lshlrev_b32_e32 v98, 16, v76
	v_and_b32_e32 v99, 0xffff0000, v76
	s_waitcnt lgkmcnt(1)
	v_pk_mul_f32 v[98:99], v[100:101], v[98:99]
	v_lshlrev_b32_e32 v100, 16, v77
	v_and_b32_e32 v101, 0xffff0000, v77
	v_pk_mul_f32 v[100:101], v[102:103], v[100:101]
	v_cvt_pk_bf16_f32 v98, v98, v99
	v_cvt_pk_bf16_f32 v99, v100, v101
	ds_read_b128 v[100:103], v91 offset:17408
	ds_read_b128 v[104:107], v91 offset:17472
	ds_read_b128 v[108:111], v91 offset:19712
	ds_read_b128 v[112:115], v91 offset:19776
	ds_read_b128 v[144:147], v91 offset:22016
	ds_read_b128 v[148:151], v91 offset:22080
	ds_read_b128 v[152:155], v91 offset:24320
	ds_read_b128 v[156:159], v89 offset:128
	ds_read_b128 v[186:189], v91 offset:24384
	s_waitcnt lgkmcnt(8)
	v_mfma_f32_16x16x32_bf16 v[100:103], v[96:99], v[100:103], 0
	v_lshlrev_b32_e32 v116, 16, v78
	v_and_b32_e32 v117, 0xffff0000, v78
	s_waitcnt lgkmcnt(1)
	v_pk_mul_f32 v[116:117], v[156:157], v[116:117]
	v_mfma_f32_16x16x32_bf16 v[108:111], v[96:99], v[108:111], 0
	v_cvt_pk_bf16_f32 v156, v116, v117
	v_lshlrev_b32_e32 v116, 16, v79
	v_and_b32_e32 v117, 0xffff0000, v79
	v_mfma_f32_16x16x32_bf16 v[144:147], v[96:99], v[144:147], 0
	v_mul_f32_e64 v116, v158, v116
	v_mul_f32_e64 v117, v159, v117
	v_mul_u32_u24_e32 v182, 0x240, v85
	v_cvt_pk_bf16_f32 v157, v116, v117
	v_mfma_f32_16x16x32_bf16 v[96:99], v[96:99], v[152:155], 0
	ds_read_b128 v[152:155], v89 offset:144
	v_lshlrev_b32_e32 v116, 16, v80
	v_and_b32_e32 v117, 0xffff0000, v80
	v_or_b32_e32 v85, 32, v93
	s_movk_i32 s7, 0x110
	s_waitcnt lgkmcnt(0)
	v_pk_mul_f32 v[116:117], v[152:153], v[116:117]
	v_mad_u32_u24 v87, v85, s7, v174
	v_cvt_pk_bf16_f32 v158, v116, v117
	v_lshlrev_b32_e32 v116, 16, v81
	v_and_b32_e32 v117, 0xffff0000, v81
	v_pk_mul_f32 v[116:117], v[154:155], v[116:117]
	s_and_b32 s7, s24, 48
	v_cvt_pk_bf16_f32 v159, v116, v117
	s_lshl_b32 s8, s97, 2
	s_and_b32 s8, s8, 0xffffff0
	v_mfma_f32_16x16x32_bf16 v[100:103], v[156:159], v[104:107], v[100:103]
	v_or_b32_e32 v91, s8, v93
	v_mul_lo_u32 v95, v91, s6
	v_readfirstlane_b32 s51, v94
	v_mfma_f32_16x16x32_bf16 v[104:107], v[156:159], v[112:115], v[108:111]
	s_nop 3
	v_cvt_pk_bf16_f32 v100, v100, v101
	v_cvt_pk_bf16_f32 v101, v102, v103
	ds_write_b64 v183, v[100:101] offset:31232
	v_mfma_f32_16x16x32_bf16 v[108:111], v[156:159], v[148:151], v[144:147]
	v_add_u32_e32 v112, 0, v95
	v_cvt_pk_bf16_f32 v100, v104, v105
	v_cvt_pk_bf16_f32 v101, v106, v107
	v_mfma_f32_16x16x32_bf16 v[96:99], v[156:159], v[186:189], v[96:99]
	ds_write_b64 v183, v[100:101] offset:35584
	s_nop 2
	v_cvt_pk_bf16_f32 v100, v108, v109
	v_cvt_pk_bf16_f32 v101, v110, v111
	ds_write_b64 v87, v[100:101] offset:31232
	v_add_u32_e32 v187, v112, v193
	v_cvt_pk_bf16_f32 v96, v96, v97
	v_cvt_pk_bf16_f32 v97, v98, v99
	ds_write_b64 v87, v[96:97] offset:35584
	v_or_b32_e32 v87, s7, v93
	v_mad_u32_u24 v89, v87, s6, 0
	v_add_u32_e32 v186, v89, v193
	ds_read_b128 v[96:99], v186 offset:17408
	ds_read_b128 v[100:103], v187 offset:26624
	ds_read_b128 v[104:107], v186 offset:17472
	ds_read_b128 v[108:111], v187 offset:26688
	s_waitcnt lgkmcnt(2)
	v_mfma_f32_16x16x32_bf16 v[94:97], v[96:99], v[100:103], 0
	s_and_b32 s8, s66, 7
	s_ashr_i32 s9, s66, 3
	s_cmp_gt_i32 s9, 15
	s_mov_b64 s[78:79], s[10:11]
	s_mov_b64 s[80:81], s[16:17]
	v_lshl_add_u64 v[152:153], s[10:11], 0, v[82:83]
	v_lshl_add_u64 v[154:155], s[16:17], 0, v[82:83]
	s_cselect_b64 s[16:17], -1, 0
	s_lshl_b32 s11, s9, 2
	v_or_b32_e32 v189, s7, v92
	s_add_i32 s11, s11, 0x7fffffc0
	v_mul_u32_u24_e32 v188, 0x110, v85
	s_waitcnt lgkmcnt(0)
	v_mfma_f32_16x16x32_bf16 v[98:101], v[104:107], v[108:111], v[94:97]
	v_mul_u32_u24_e32 v85, 0x1800, v189
	s_lshl_b32 s10, s8, 6
	s_and_b32 s46, s11, 0x7ffffff0
	v_mul_u32_u24_e32 v113, 0x90, v93
	v_mul_u32_u24_e32 v102, 0x90, v87
	s_waitcnt lgkmcnt(0)
	s_barrier
	v_lshl_add_u32 v94, v91, 7, v112
	v_mul_u32_u24_e32 v95, 0x110, v87
	v_lshl_add_u32 v96, v87, 7, v89
	v_lshlrev_b32_e32 v97, 1, v189
	v_add_lshl_u32 v92, v85, v91, 1
	v_mov_b32_e32 v93, v127
	v_mov_b32_e32 v85, v127
	v_mov_b32_e32 v87, v127
	v_mov_b32_e32 v89, v127
	v_mov_b32_e32 v91, v127
	s_add_i32 s46, s46, s10
	s_and_b32 s10, s9, 3
	s_lshl_b32 s8, s8, 4
	s_and_b32 s9, s9, -4
	v_mbcnt_lo_u32_b32 v82, -1, 0
	v_lshlrev_b64 v[144:145], 9, v[84:85]
	v_lshlrev_b64 v[146:147], 9, v[86:87]
	v_lshlrev_b64 v[148:149], 9, v[88:89]
	v_lshlrev_b64 v[150:151], 9, v[90:91]
	s_add_i32 s8, s8, s9
	v_add3_u32 v190, s49, v95, v193
	v_add3_u32 v191, s50, v102, v193
	v_lshl_add_u64 v[156:157], s[0:1], 0, v[92:93]
	v_mov_b32_e32 v243, v92
	v_add_u32_e32 v244, 0x3000, v92
	v_add_u32_e32 v245, 0x6000, v92
	v_add_u32_e32 v246, 0x9000, v92
	v_add_u32_e32 v192, v94, v193
	v_add_u32_e32 v193, v96, v193
	v_add_u32_e32 v194, v112, v97
	v_mbcnt_hi_u32_b32 v195, -1, v82
	v_mov_b64_e32 v[84:85], v[24:25]
	v_mov_b64_e32 v[88:89], v[20:21]
	v_mov_b64_e32 v[92:93], v[16:17]
	v_mov_b64_e32 v[96:97], v[12:13]
	s_mov_b32 s15, 0
	s_mov_b32 s58, 2
	s_mov_b32 s45, 1
	v_mov_b32_e32 v121, v127
	v_cmp_eq_u32_e64 s[6:7], 0, v0
	s_mov_b32 s96, s66
	s_or_b32 s47, s10, 0x80
	s_or_b32 s48, s8, s10
	s_movk_i32 s49, 0x2000
	s_movk_i32 s50, 0x3000
	s_mov_b64 s[18:19], 0x4000000
	v_mov_b32_e32 v158, 0
	v_add_u32_e32 v196, v196, v113
	v_mov_b64_e32 v[82:83], v[22:23]
	v_mov_b64_e32 v[86:87], v[18:19]
	v_mov_b64_e32 v[90:91], v[14:15]
	v_mov_b64_e32 v[94:95], v[10:11]
	s_mov_b32 s54, 0
	s_mov_b32 s8, 1
	s_mov_b32 s56, 0
	s_mov_b32 s63, 0
	s_mov_b32 s62, s29
	s_mov_b32 s60, s27
	s_mov_b32 s61, s28
	s_mov_b32 s57, s26
	s_mov_b32 s59, s51
	s_mov_b32 s24, 1
	s_mov_b32 s86, s51
	s_mov_b32 s85, s26
	s_mov_b32 s84, s28
	s_mov_b32 s83, s27
	s_mov_b32 s82, s29
	s_mov_b32 s25, 0
	s_mov_b32 s52, 0
	s_branch .Lp4n_entry

.Lp4n_tab:
	v_mbcnt_lo_u32_b32 v229, -1, 0
	v_mbcnt_hi_u32_b32 v229, -1, v229
	v_and_b32_e32 v230, s61, v229
	v_lshrrev_b32_e32 v231, s62, v229
	v_lshrrev_b32_e32 v232, 1, v231
	v_add_u32_e32 v232, s59, v232
	v_and_b32_e32 v232, 7, v232
	v_add_u32_e32 v233, s60, v231
	v_and_b32_e32 v233, 1, v233
	v_sub_u32_e32 v234, s61, v230
	v_cmp_eq_u32_e32 vcc, 1, v233
	s_nop 1
	v_cndmask_b32_e32 v235, v230, v234, vcc
	v_add_u32_e32 v235, s64, v235
	v_cmp_eq_u32_e32 vcc, s61, v230
	s_nop 1
	v_cndmask_b32_e64 v236, 0, 1, vcc
	v_lshlrev_b32_e32 v237, 9, v232
	v_or_b32_e32 v220, v235, v237
	v_lshlrev_b32_e32 v237, 12, v233
	v_or_b32_e32 v220, v220, v237
	s_lshl_b32 s45, s57, 13
	s_lshl_b32 s46, s58, 15
	s_or_b32 s45, s45, s46
	s_lshl_b32 s46, s63, 20
	s_or_b32 s45, s45, s46
	v_or_b32_e32 v220, s45, v220
	v_lshlrev_b32_e32 v237, 21, v236
	v_or_b32_e32 v220, v220, v237
	v_lshlrev_b32_e32 v237, 22, v230
	v_or_b32_e32 v220, v220, v237
	v_lshl_add_u32 v237, v235, 3, v232
	v_lshlrev_b32_e32 v221, 14, v237
	v_lshlrev_b32_e32 v238, 8, v233
	v_lshl_add_u32 v224, v237, 10, v238
	v_lshlrev_b32_e32 v238, 8, v232
	v_lshl_add_u32 v222, v235, 17, v238
	s_mov_b32 s45, 0xc0000
	v_mul_lo_u32 v237, v235, s45
	s_lshl_b32 s46, s57, 6
	s_sub_u32 s46, s46, 0x5000
	v_add_u32_e32 v238, s46, v238
	v_add_u32_e32 v223, v237, v238
	s_mov_b32 s45, 0x60000
	v_mul_lo_u32 v237, v235, s45
	v_lshlrev_b32_e32 v238, 10, v233
	v_lshl_add_u32 v238, v232, 7, v238
	s_lshl_b32 s46, s57, 5
	v_add_u32_e32 v238, s46, v238
	v_add_u32_e32 v227, v237, v238
	v_lshlrev_b32_e32 v228, 6, v235
	v_mov_b32_e32 v225, s65
	v_mov_b32_e32 v226, s66
	s_mov_b32 s99, 0
	v_lshlrev_b32_e32 v239, 4, v0
	v_add_u32_e32 v240, 0x2000, v239
	v_mov_b32_e32 v241, v118
	v_add_u32_e32 v242, 0x10000, v118
	s_mov_b32 s100, 0xbfb8aa3b
	s_mov_b32 s101, 0xbfb8aa3b
	s_nop 1
	v_readlane_b32 s41, v220, 0
	v_readlane_b32 s42, v220, 1
	v_readlane_b32 s43, v220, 2

.Lp4n_nocwn_A:
	s_cmp_lt_u32 s99, 61
	s_cbranch_scc0 .Lp4n_premid_A
	s_add_u32 s46, s99, 3
	s_nop 3
	v_readlane_b32 s8, v221, s46
	v_readlane_b32 s88, v222, s46
	v_readlane_b32 s20, v223, s46
	v_readlane_b32 s47, v224, s46
	v_readlane_b32 s76, v225, s46
	v_readlane_b32 s77, v226, s46
	v_readlane_b32 s22, v228, s46
	v_readlane_b32 s44, v220, s46
	s_add_u32 s88, s72, s88
	s_addc_u32 s89, s73, 0
	s_add_u32 s90, s78, s8
	s_addc_u32 s91, s79, 0
	s_add_u32 s92, s80, s8
	s_addc_u32 s93, s81, 0
	global_load_dwordx4 v[26:29], v239, s[90:91]
	global_load_dwordx4 v[30:33], v240, s[90:91]
	global_load_dwordx4 v[34:37], v241, s[88:89]
	global_load_dwordx4 v[38:41], v242, s[88:89]
	global_load_dwordx4 v[42:45], v239, s[92:93]
	global_load_dwordx4 v[46:49], v240, s[92:93]
	s_ashr_i32 s89, s20, 31
	s_add_u32 s88, s0, s20
	s_addc_u32 s89, s1, s89
	s_bfe_u32 s45, s44, 0x60016
	s_cmp_eq_u32 s45, 0
	s_cbranch_scc1 .Lp4n_vedge_A
	s_bfe_u32 s45, s44, 0x10015
	s_cmp_lg_u32 s45, 0
	s_cbranch_scc1 .Lp4n_vedge_A
	global_load_dwordx2 v[128:129], v120, s[88:89]
	s_add_u32 s90, s88, 0x3000
	s_addc_u32 s91, s89, 0
	global_load_dwordx2 v[130:131], v120, s[90:91]
	s_add_u32 s90, s88, 0x6000
	s_addc_u32 s91, s89, 0
	global_load_dwordx2 v[132:133], v120, s[90:91]
	s_add_u32 s90, s88, 0x9000
	s_addc_u32 s91, s89, 0
	global_load_dwordx2 v[136:137], v120, s[90:91]
	s_branch .Lp4n_vdone_A

.Lp4n_premid_A:
.Lp4n_mid_A:
	s_waitcnt lgkmcnt(0)
	s_barrier
	v_mov_b32_e32 v102, s87
	ds_read_b32 v198, v102 offset:768
	ds_read_b128 v[102:105], v196 offset:61952
	ds_read_b128 v[106:109], v196 offset:64256
	s_waitcnt lgkmcnt(2)
	v_pk_mul_f32 v[4:5], v[4:5], v[198:199] op_sel_hi:[1,0]
	v_pk_mul_f32 v[2:3], v[2:3], v[198:199] op_sel_hi:[1,0]
	v_pk_mul_f32 v[8:9], v[8:9], v[198:199] op_sel_hi:[1,0]
	v_pk_mul_f32 v[6:7], v[6:7], v[198:199] op_sel_hi:[1,0]
	s_waitcnt lgkmcnt(1)
	v_mfma_f32_16x16x32_bf16 v[2:5], v[74:77], v[102:105], v[2:5]
	ds_read_b128 v[102:105], v196 offset:62016
	s_waitcnt lgkmcnt(1)
	v_mfma_f32_16x16x32_bf16 v[6:9], v[74:77], v[106:109], v[6:9]
	v_readlane_b32 s8, v227, s99
	s_lshl_b32 s8, s8, 1
	s_add_u32 s8, s0, s8
	s_addc_u32 s9, s1, 0
	s_waitcnt lgkmcnt(0)
	v_mfma_f32_16x16x32_bf16 v[102:105], v[78:81], v[102:105], v[2:5]
	s_nop 2
	ds_read_b128 v[2:5], v196 offset:64320
	ds_read_b128 v[198:201], v191
	ds_read_b128 v[202:205], v187 offset:57344
	s_waitcnt lgkmcnt(2)
	v_mfma_f32_16x16x32_bf16 v[106:109], v[78:81], v[2:5], v[6:9]
	v_mul_f32_e64 v4, v116, v112
	v_mul_f32_e64 v5, v117, v113
	v_pk_mul_f32 v[2:3], v[114:115], v[110:111]
	ds_read_b128 v[110:113], v191 offset:64
	ds_read_b128 v[6:9], v187 offset:57408
	s_waitcnt lgkmcnt(2)
	v_mfma_f32_16x16x32_bf16 v[2:5], v[198:201], v[202:205], v[2:5]
	s_bfe_u32 s45, s41, 0x10015
	s_cmp_eq_u32 s45, 0
	s_waitcnt lgkmcnt(0)
	v_mfma_f32_16x16x32_bf16 v[2:5], v[110:113], v[6:9], v[2:5]
	s_nop 7
	v_cvt_pk_bf16_f32 v2, v2, s0
	global_store_short v243, v2, s[8:9]
	v_cvt_pk_bf16_f32 v8, v3, s0
	global_store_short v244, v8, s[8:9]
	v_cvt_pk_bf16_f32 v4, v4, s0
	global_store_short v245, v4, s[8:9]
	v_cvt_pk_bf16_f32 v3, v5, s0
	global_store_short v246, v3, s[8:9]
	s_cbranch_scc1 .Lp4n_sjoin_A
	s_bfe_u32 s45, s41, 0x10014
	s_cmp_lg_u32 s45, 0
	s_cbranch_scc1 .Lp4n_nosst_A
	s_bfe_u32 s8, s41, 0x5000f
	s_lshl_b32 s8, s8, 4
	s_bfe_u32 s9, s41, 0x1000c
	s_lshl_b32 s9, s9, 3
	s_bfe_u32 s14, s41, 0x30009
	s_add_i32 s8, s14, s8
	s_bfe_u32 s14, s41, 0x2000d
	s_lshl_b32 s14, s14, 5
	s_add_i32 s8, s8, s9
	s_ashr_i32 s9, s8, 31
	s_lshl_b64 s[8:9], s[8:9], 16
	s_add_u32 s20, s72, s8
	s_addc_u32 s21, s73, s9
	s_lshl_b64 s[8:9], s[14:15], 2
	s_add_u32 s8, s20, s8
	s_addc_u32 s9, s21, s9
	v_lshl_add_u64 v[2:3], s[8:9], 0, v[126:127]
	v_lshl_add_u64 v[2:3], v[2:3], 0, s[18:19]
	v_lshl_add_u64 v[4:5], v[2:3], 0, v[144:145]
	v_lshl_add_u64 v[6:7], v[2:3], 0, v[146:147]
	v_lshl_add_u64 v[8:9], v[2:3], 0, v[148:149]
	v_lshl_add_u64 v[2:3], v[2:3], 0, v[150:151]
	global_store_dword v[4:5], v102, off
	global_store_dword v[6:7], v103, off
	global_store_dword v[8:9], v104, off
	global_store_dword v[2:3], v105, off
	global_store_dword v[4:5], v106, off offset:64
	global_store_dword v[6:7], v107, off offset:64
	global_store_dword v[8:9], v108, off offset:64
	global_store_dword v[2:3], v109, off offset:64

.Lp4n_nocwn_B:
	s_cmp_lt_u32 s99, 61
	s_cbranch_scc0 .Lp4n_premid_B
	s_add_u32 s46, s99, 3
	s_nop 3
	v_readlane_b32 s8, v221, s46
	v_readlane_b32 s88, v222, s46
	v_readlane_b32 s20, v223, s46
	v_readlane_b32 s47, v224, s46
	v_readlane_b32 s76, v225, s46
	v_readlane_b32 s77, v226, s46
	v_readlane_b32 s22, v228, s46
	v_readlane_b32 s44, v220, s46
	s_add_u32 s88, s72, s88
	s_addc_u32 s89, s73, 0
	s_add_u32 s90, s78, s8
	s_addc_u32 s91, s79, 0
	s_add_u32 s92, s80, s8
	s_addc_u32 s93, s81, 0
	global_load_dwordx4 v[50:53], v239, s[90:91]
	global_load_dwordx4 v[54:57], v240, s[90:91]
	global_load_dwordx4 v[58:61], v241, s[88:89]
	global_load_dwordx4 v[62:65], v242, s[88:89]
	global_load_dwordx4 v[66:69], v239, s[92:93]
	global_load_dwordx4 v[70:73], v240, s[92:93]
	s_ashr_i32 s89, s20, 31
	s_add_u32 s88, s0, s20
	s_addc_u32 s89, s1, s89
	s_bfe_u32 s45, s44, 0x60016
	s_cmp_eq_u32 s45, 0
	s_cbranch_scc1 .Lp4n_vedge_B
	s_bfe_u32 s45, s44, 0x10015
	s_cmp_lg_u32 s45, 0
	s_cbranch_scc1 .Lp4n_vedge_B
	global_load_dwordx2 v[134:135], v120, s[88:89]
	s_add_u32 s90, s88, 0x3000
	s_addc_u32 s91, s89, 0
	global_load_dwordx2 v[138:139], v120, s[90:91]
	s_add_u32 s90, s88, 0x6000
	s_addc_u32 s91, s89, 0
	global_load_dwordx2 v[140:141], v120, s[90:91]
	s_add_u32 s90, s88, 0x9000
	s_addc_u32 s91, s89, 0
	global_load_dwordx2 v[142:143], v120, s[90:91]
	s_branch .Lp4n_vdone_B

.Lp4n_premid_B:
.Lp4n_mid_B:
	s_waitcnt lgkmcnt(0)
	s_barrier
	v_mov_b32_e32 v2, s87
	ds_read_b32 v198, v2 offset:768
	ds_read_b128 v[2:5], v196 offset:61952
	ds_read_b128 v[6:9], v196 offset:64256
	v_add_u32_e32 v159, 0x2400, v191
	s_waitcnt lgkmcnt(2)
	v_pk_mul_f32 v[104:105], v[104:105], v[198:199] op_sel_hi:[1,0]
	v_pk_mul_f32 v[102:103], v[102:103], v[198:199] op_sel_hi:[1,0]
	v_pk_mul_f32 v[108:109], v[108:109], v[198:199] op_sel_hi:[1,0]
	v_pk_mul_f32 v[106:107], v[106:107], v[198:199] op_sel_hi:[1,0]
	s_waitcnt lgkmcnt(1)
	v_mfma_f32_16x16x32_bf16 v[102:105], v[74:77], v[2:5], v[102:105]
	ds_read_b128 v[2:5], v196 offset:62016
	s_waitcnt lgkmcnt(1)
	v_mfma_f32_16x16x32_bf16 v[106:109], v[74:77], v[6:9], v[106:109]
	v_readlane_b32 s8, v227, s99
	s_lshl_b32 s8, s8, 1
	s_add_u32 s8, s0, s8
	s_addc_u32 s9, s1, 0
	s_waitcnt lgkmcnt(0)
	v_mfma_f32_16x16x32_bf16 v[2:5], v[78:81], v[2:5], v[102:105]
	s_nop 2
	ds_read_b128 v[102:105], v196 offset:64320
	ds_read_b128 v[198:201], v159
	ds_read_b128 v[202:205], v187 offset:57344
	s_waitcnt lgkmcnt(2)
	v_mfma_f32_16x16x32_bf16 v[6:9], v[78:81], v[102:105], v[106:109]
	v_mul_f32_e64 v104, v116, v112
	v_mul_f32_e64 v105, v117, v113
	v_pk_mul_f32 v[102:103], v[114:115], v[110:111]
	ds_read_b128 v[110:113], v159 offset:64
	ds_read_b128 v[106:109], v187 offset:57408
	s_waitcnt lgkmcnt(2)
	v_mfma_f32_16x16x32_bf16 v[102:105], v[198:201], v[202:205], v[102:105]
	s_bfe_u32 s45, s41, 0x10015
	s_cmp_eq_u32 s45, 0
	s_waitcnt lgkmcnt(0)
	v_mfma_f32_16x16x32_bf16 v[102:105], v[110:113], v[106:109], v[102:105]
	s_nop 7
	v_cvt_pk_bf16_f32 v102, v102, s0
	global_store_short v243, v102, s[8:9]
	v_cvt_pk_bf16_f32 v108, v103, s0
	global_store_short v244, v108, s[8:9]
	v_cvt_pk_bf16_f32 v104, v104, s0
	global_store_short v245, v104, s[8:9]
	v_cvt_pk_bf16_f32 v103, v105, s0
	global_store_short v246, v103, s[8:9]
	s_cbranch_scc1 .Lp4n_sjoin_B
	s_bfe_u32 s45, s41, 0x10014
	s_cmp_lg_u32 s45, 0
	s_cbranch_scc1 .Lp4n_nosst_B
	s_bfe_u32 s8, s41, 0x5000f
	s_lshl_b32 s8, s8, 4
	s_bfe_u32 s9, s41, 0x1000c
	s_lshl_b32 s9, s9, 3
	s_bfe_u32 s14, s41, 0x30009
	s_add_i32 s8, s14, s8
	s_bfe_u32 s14, s41, 0x2000d
	s_lshl_b32 s14, s14, 5
	s_add_i32 s8, s8, s9
	s_ashr_i32 s9, s8, 31
	s_lshl_b64 s[8:9], s[8:9], 16
	s_add_u32 s20, s72, s8
	s_addc_u32 s21, s73, s9
	s_lshl_b64 s[8:9], s[14:15], 2
	s_add_u32 s8, s20, s8
	s_addc_u32 s9, s21, s9
	v_lshl_add_u64 v[102:103], s[8:9], 0, v[126:127]
	v_lshl_add_u64 v[102:103], v[102:103], 0, s[18:19]
	v_lshl_add_u64 v[104:105], v[102:103], 0, v[144:145]
	v_lshl_add_u64 v[106:107], v[102:103], 0, v[146:147]
	v_lshl_add_u64 v[108:109], v[102:103], 0, v[148:149]
	v_lshl_add_u64 v[102:103], v[102:103], 0, v[150:151]
	global_store_dword v[104:105], v2, off
	global_store_dword v[106:107], v3, off
	global_store_dword v[108:109], v4, off
	global_store_dword v[102:103], v5, off
	global_store_dword v[104:105], v6, off offset:64
	global_store_dword v[106:107], v7, off offset:64
	global_store_dword v[108:109], v8, off offset:64
	global_store_dword v[102:103], v9, off offset:64
